# gemm prologue: the three buf[1] stages are issued before the first wait+barrier (vmcnt 4 -> 10), overlapping the two start-up round trips
# speedup vs baseline: 1.0044x; 1.0044x over previous
; __device__ __forceinline__ int opaque_tid() { int t; asm volatile("v_mov_b32 %0, %1" : "=v"(t) : "v"((int)threadIdx.x)); return t; }
; #define PG8_STAGE(bufoff, gbase, voff) do { _Pragma("unroll") for (int _i = 0; _i < 2; ++_i) \
;         __builtin_amdgcn_global_load_lds((const unsigned*)((const char*)(gbase) + (voff)[_i]), (PG8_LAS unsigned*)(lds + (bufoff) + ldsw + _i * 8192), 16, 0, 0); } while (0)
; #define PG8_WAIT_V(n) asm volatile("s_waitcnt vmcnt(" #n ")" ::: "memory")
; #define PG8_BAR __builtin_amdgcn_s_barrier()
; template <class Epi, class Sched>
; __device__ __forceinline__ void gemm_phase(PG8_LAS unsigned char* lds, const Gemm g, const Sched& S, const Epi& E) {
;     const int tid = opaque_tid(), wid = __builtin_amdgcn_readfirstlane(tid >> 6), lane = tid & 63, wr = wid >> 2, wc = wid & 3, fr = lane & 15, fq = lane >> 4;
;     const int K = g.K, nt = K / BK, P = g.ldk ? g.ldk : K;
;     unsigned voffA[2], voffB[2];
; #pragma unroll
;     for (int i = 0; i < 2; ++i) { int R, C; stage_rc(tid * 16 + i * 8192, R, C); const int Rb = Epi::PERM ? ((R & ~31) + perm32(R & 31)) : R;
;         voffA[i] = (unsigned)(R * P + C) * 2u; voffB[i] = (unsigned)(Rb * P + C) * 2u; }
;     const size_t kstep = (size_t)(BK * 2);
;     const size_t hstep = (size_t)HALF * P * 2;
;     const size_t tstep = 2 * hstep; const size_t tstepA = g.a_step_rows ? (size_t)g.a_step_rows * P * 2 : tstep; const size_t cstep = (size_t)K * 2;
;     const unsigned ldsw = (unsigned)wid * 1024u;
;     const int aoff = lds_byte(wr * 64 + fr, fq * 8), boff = lds_byte(wc * 32 + fr, fq * 8);
;     ...
;     const char* cA = (const char*)g.A + (size_t)cur.pm * tstepA + (size_t)cur.kc * cstep; const char* cB = (const char*)g.Bt + (size_t)cur.pn * tstep + (size_t)cur.kc * cstep;
;     S.a_ready(cur);
;     PG8_STAGE(PG8_SB(0, 0), cB, voffB); PG8_STAGE(PG8_SA(0, 0), cA, voffA); PG8_STAGE(PG8_SB(0, 1), cB + hstep, voffB); PG8_STAGE(PG8_SA(0, 1), cA + hstep, voffA);
;     if (wr == 1) PG8_BAR;
;     PG8_WAIT_V(4); PG8_BAR;
;     PG8_STAGE(PG8_SB(1, 0), cB + kstep, voffB); PG8_STAGE(PG8_SA(1, 0), cA + kstep, voffA); PG8_STAGE(PG8_SB(1, 1), cB + hstep + kstep, voffB);
;     PG8_WAIT_V(6); PG8_BAR;
.LBB0_255:
	s_mul_i32 s24, s61, 0x36000
	s_sext_i32_i8 s70, s23
	s_mul_hi_i32 s23, s61, 0x36000
	s_add_u32 s24, s50, s24
	s_addc_u32 s23, s51, s23
	s_lshl_b32 s12, s12, 2
	v_bfe_u32 v19, v18, 4, 2
	s_add_u32 s46, s24, s12
	v_and_b32_e32 v21, 15, v18
	v_lshlrev_b32_e32 v22, 4, v19
	v_lshlrev_b32_e32 v18, 2, v18
	s_addc_u32 s47, s23, 0
	v_lshl_or_b32 v20, s13, 6, v21
	v_lshl_or_b32 v21, v21, 6, v22
	s_lshl_b32 s12, s13, 13
	v_and_b32_e32 v18, 32, v18
	v_bitop3_b32 v22, v21, s12, v18 bitop3:0xde
	s_lshl_b32 s12, s22, 5
	s_and_b32 s12, s12, 0x60
	s_lshr_b32 s54, s29, 6
	s_lshl_b32 s13, s12, 7
	s_add_u32 s55, s50, 0xa00000
	v_bitop3_b32 v170, v21, s13, v18 bitop3:0xde
	s_addc_u32 s56, s51, 0
	s_or_b32 s13, s62, s61
	s_cmp_eq_u32 s13, 0
	s_waitcnt lgkmcnt(0)
	s_cselect_b32 s59, s3, s49
	s_cselect_b32 s63, s2, s48
	s_add_i32 m0, s36, 0x18000
	v_lshl_add_u64 v[0:1], v[0:1], 0, s[0:1]
	global_load_lds_dwordx4 v[0:1], off
	v_lshl_add_u64 v[0:1], v[2:3], 0, s[0:1]
	s_add_i32 m0, s36, 0x1a000
	s_add_i32 s64, s36, 0x8000
	global_load_lds_dwordx4 v[0:1], off
	v_lshl_add_u64 v[0:1], v[4:5], 0, s[0:1]
	s_mov_b32 m0, s64
	s_add_i32 s65, s36, 0xa000
	global_load_lds_dwordx4 v[0:1], off
	v_lshl_add_u64 v[0:1], v[6:7], 0, s[0:1]
	s_mov_b32 m0, s65
	v_ashrrev_i32_e32 v21, 31, v20
	global_load_lds_dwordx4 v[0:1], off
	s_add_i32 m0, s36, 0x1c000
	v_lshl_add_u64 v[0:1], v[8:9], 0, s[0:1]
	global_load_lds_dwordx4 v[0:1], off
	v_lshl_add_u64 v[0:1], v[10:11], 0, s[0:1]
	s_add_i32 m0, s36, 0x1e000
	v_lshlrev_b64 v[148:149], 10, v[20:21]
	global_load_lds_dwordx4 v[0:1], off
	s_waitcnt vmcnt(10)
	s_barrier
	v_or_b32_e32 v0, 16, v20
	v_ashrrev_i32_e32 v1, 31, v0
	v_lshlrev_b64 v[150:151], 10, v[0:1]
	v_or_b32_e32 v0, 32, v20
	v_ashrrev_i32_e32 v1, 31, v0
	v_lshlrev_b64 v[152:153], 10, v[0:1]
	v_or_b32_e32 v0, 48, v20
	v_ashrrev_i32_e32 v1, 31, v0
	v_lshlrev_b64 v[154:155], 10, v[0:1]
	s_mov_b64 s[2:3], 0x20000
	v_add_u32_e32 v0, v14, v12
	v_lshl_add_u64 v[156:157], v[148:149], 0, s[2:3]
	s_mov_b64 s[2:3], 0x24000
	v_add_lshl_u32 v0, v0, v13, 1
	v_mov_b32_e32 v1, v49
	s_waitcnt vmcnt(6)
	v_lshl_add_u64 v[158:159], v[148:149], 0, s[2:3]
	s_mov_b64 s[2:3], 0x28000
	v_lshl_add_u64 v[164:165], s[10:11], 0, v[0:1]
	v_add_u32_e32 v0, v17, v15
	v_lshl_add_u64 v[160:161], v[148:149], 0, s[2:3]
	s_mov_b64 s[2:3], 0x2c000
	v_add_lshl_u32 v0, v0, v16, 1
	s_mov_b32 s57, 0
	s_add_i32 s66, s54, -2
	v_lshl_add_u64 v[162:163], v[148:149], 0, s[2:3]
	v_lshl_or_b32 v171, v19, 2, s12
	v_lshl_add_u64 v[166:167], s[10:11], 0, v[0:1]
	v_add_u32_e32 v172, 0, v22
	s_barrier
	s_branch .LBB0_257

; __device__ __forceinline__ int opaque_tid() { int t; asm volatile("v_mov_b32 %0, %1" : "=v"(t) : "v"((int)threadIdx.x)); return t; }
; #define PG8_STAGE(bufoff, gbase, voff) do { _Pragma("unroll") for (int _i = 0; _i < 2; ++_i) \
;         __builtin_amdgcn_global_load_lds((const unsigned*)((const char*)(gbase) + (voff)[_i]), (PG8_LAS unsigned*)(lds + (bufoff) + ldsw + _i * 8192), 16, 0, 0); } while (0)
; #define PG8_WAIT_V(n) asm volatile("s_waitcnt vmcnt(" #n ")" ::: "memory")
; #define PG8_BAR __builtin_amdgcn_s_barrier()
; template <class Epi, class Sched>
; __device__ __forceinline__ void gemm_phase(PG8_LAS unsigned char* lds, const Gemm g, const Sched& S, const Epi& E) {
;     const int tid = opaque_tid(), wid = __builtin_amdgcn_readfirstlane(tid >> 6), lane = tid & 63, wr = wid >> 2, wc = wid & 3, fr = lane & 15, fq = lane >> 4;
;     const int K = g.K, nt = K / BK, P = g.ldk ? g.ldk : K;
;     unsigned voffA[2], voffB[2];
; #pragma unroll
;     for (int i = 0; i < 2; ++i) { int R, C; stage_rc(tid * 16 + i * 8192, R, C); const int Rb = Epi::PERM ? ((R & ~31) + perm32(R & 31)) : R;
;         voffA[i] = (unsigned)(R * P + C) * 2u; voffB[i] = (unsigned)(Rb * P + C) * 2u; }
;     const size_t kstep = (size_t)(BK * 2);
;     const size_t hstep = (size_t)HALF * P * 2;
;     const size_t tstep = 2 * hstep; const size_t tstepA = g.a_step_rows ? (size_t)g.a_step_rows * P * 2 : tstep; const size_t cstep = (size_t)K * 2;
;     const unsigned ldsw = (unsigned)wid * 1024u;
;     const int aoff = lds_byte(wr * 64 + fr, fq * 8), boff = lds_byte(wc * 32 + fr, fq * 8);
;     ...
;     const char* cA = (const char*)g.A + (size_t)cur.pm * tstepA + (size_t)cur.kc * cstep; const char* cB = (const char*)g.Bt + (size_t)cur.pn * tstep + (size_t)cur.kc * cstep;
;     S.a_ready(cur);
;     PG8_STAGE(PG8_SB(0, 0), cB, voffB); PG8_STAGE(PG8_SA(0, 0), cA, voffA); PG8_STAGE(PG8_SB(0, 1), cB + hstep, voffB); PG8_STAGE(PG8_SA(0, 1), cA + hstep, voffA);
;     if (wr == 1) PG8_BAR;
;     PG8_WAIT_V(4); PG8_BAR;
;     PG8_STAGE(PG8_SB(1, 0), cB + kstep, voffB); PG8_STAGE(PG8_SA(1, 0), cA + kstep, voffA); PG8_STAGE(PG8_SB(1, 1), cB + hstep + kstep, voffB);
;     PG8_WAIT_V(6); PG8_BAR;
.LBB0_280:
	s_add_u32 s48, s50, 0x1ca00000
	s_addc_u32 s49, s51, 0
	s_add_i32 m0, s43, 0x18000
	v_lshl_add_u64 v[0:1], v[0:1], 0, s[0:1]
	global_load_lds_dwordx4 v[0:1], off
	v_lshl_add_u64 v[0:1], v[2:3], 0, s[0:1]
	s_add_i32 m0, s43, 0x1a000
	s_add_i32 s50, s43, 0x8000
	global_load_lds_dwordx4 v[0:1], off
	v_lshl_add_u64 v[0:1], v[4:5], 0, s[0:1]
	s_mov_b32 m0, s50
	s_add_i32 s51, s43, 0xa000
	global_load_lds_dwordx4 v[0:1], off
	v_lshl_add_u64 v[0:1], v[6:7], 0, s[0:1]
	s_mov_b32 m0, s51
	v_bfe_u32 v4, v12, 4, 2
	global_load_lds_dwordx4 v[0:1], off
	s_add_i32 m0, s43, 0x1c000
	v_lshl_add_u64 v[0:1], v[8:9], 0, s[0:1]
	global_load_lds_dwordx4 v[0:1], off
	v_lshl_add_u64 v[0:1], v[10:11], 0, s[0:1]
	s_add_i32 m0, s43, 0x1e000
	v_lshlrev_b32_e32 v2, 4, v4
	global_load_lds_dwordx4 v[0:1], off
	s_waitcnt vmcnt(10)
	s_barrier
	v_and_b32_e32 v1, 15, v12
	v_lshl_or_b32 v0, s7, 6, v1
	v_lshl_or_b32 v1, v1, 6, v2
	v_lshlrev_b32_e32 v2, 2, v12
	s_lshl_b32 s3, s3, 5
	s_lshr_b32 s54, s6, 6
	s_lshl_b32 s6, s7, 13
	v_and_b32_e32 v2, 32, v2
	s_and_b32 s3, s3, 0x60
	v_bitop3_b32 v5, v1, s6, v2 bitop3:0xde
	s_lshl_b32 s6, s3, 7
	v_bitop3_b32 v152, v1, s6, v2 bitop3:0xde
	v_or_b32_e32 v2, 16, v0
	v_ashrrev_i32_e32 v1, 31, v0
	v_ashrrev_i32_e32 v3, 31, v2
	v_lshlrev_b64 v[132:133], 12, v[0:1]
	v_lshlrev_b64 v[134:135], 12, v[2:3]
	v_or_b32_e32 v2, 32, v0
	v_or_b32_e32 v0, 48, v0
	v_ashrrev_i32_e32 v1, 31, v0
	v_lshlrev_b64 v[138:139], 12, v[0:1]
	s_mov_b64 s[6:7], 0x80000
	v_add_u32_e32 v0, v16, v17
	v_lshl_add_u64 v[140:141], v[132:133], 0, s[6:7]
	s_mov_b64 s[6:7], 0x90000
	v_add_lshl_u32 v0, v0, v18, 1
	v_mov_b32_e32 v1, v49
	s_waitcnt vmcnt(6)
	v_lshl_add_u64 v[142:143], v[132:133], 0, s[6:7]
	s_mov_b64 s[6:7], 0xa0000
	v_lshl_add_u64 v[148:149], s[10:11], 0, v[0:1]
	v_add_u32_e32 v0, v13, v14
	v_ashrrev_i32_e32 v3, 31, v2
	v_lshl_add_u64 v[144:145], v[132:133], 0, s[6:7]
	s_mov_b64 s[6:7], 0xb0000
	v_add_lshl_u32 v0, v0, v15, 1
	s_add_i32 s55, s54, -2
	v_lshlrev_b64 v[136:137], 12, v[2:3]
	v_lshl_add_u64 v[146:147], v[132:133], 0, s[6:7]
	v_lshl_or_b32 v153, v4, 2, s3
	v_lshl_add_u64 v[150:151], s[10:11], 0, v[0:1]
	s_mov_b32 s11, 0
	v_add_u32_e32 v154, 0, v5
	s_barrier
	s_waitcnt vmcnt(0)

; __device__ __forceinline__ int opaque_tid() { int t; asm volatile("v_mov_b32 %0, %1" : "=v"(t) : "v"((int)threadIdx.x)); return t; }
; #define PG8_STAGE(bufoff, gbase, voff) do { _Pragma("unroll") for (int _i = 0; _i < 2; ++_i) \
;         __builtin_amdgcn_global_load_lds((const unsigned*)((const char*)(gbase) + (voff)[_i]), (PG8_LAS unsigned*)(lds + (bufoff) + ldsw + _i * 8192), 16, 0, 0); } while (0)
; #define PG8_WAIT_V(n) asm volatile("s_waitcnt vmcnt(" #n ")" ::: "memory")
; #define PG8_BAR __builtin_amdgcn_s_barrier()
; template <class Epi, class Sched>
; __device__ __forceinline__ void gemm_phase(PG8_LAS unsigned char* lds, const Gemm g, const Sched& S, const Epi& E) {
;     const int tid = opaque_tid(), wid = __builtin_amdgcn_readfirstlane(tid >> 6), lane = tid & 63, wr = wid >> 2, wc = wid & 3, fr = lane & 15, fq = lane >> 4;
;     const int K = g.K, nt = K / BK, P = g.ldk ? g.ldk : K;
;     unsigned voffA[2], voffB[2];
; #pragma unroll
;     for (int i = 0; i < 2; ++i) { int R, C; stage_rc(tid * 16 + i * 8192, R, C); const int Rb = Epi::PERM ? ((R & ~31) + perm32(R & 31)) : R;
;         voffA[i] = (unsigned)(R * P + C) * 2u; voffB[i] = (unsigned)(Rb * P + C) * 2u; }
;     const size_t kstep = (size_t)(BK * 2);
;     const size_t hstep = (size_t)HALF * P * 2;
;     const size_t tstep = 2 * hstep; const size_t tstepA = g.a_step_rows ? (size_t)g.a_step_rows * P * 2 : tstep; const size_t cstep = (size_t)K * 2;
;     const unsigned ldsw = (unsigned)wid * 1024u;
;     const int aoff = lds_byte(wr * 64 + fr, fq * 8), boff = lds_byte(wc * 32 + fr, fq * 8);
;     ...
;     const char* cA = (const char*)g.A + (size_t)cur.pm * tstepA + (size_t)cur.kc * cstep; const char* cB = (const char*)g.Bt + (size_t)cur.pn * tstep + (size_t)cur.kc * cstep;
;     S.a_ready(cur);
;     PG8_STAGE(PG8_SB(0, 0), cB, voffB); PG8_STAGE(PG8_SA(0, 0), cA, voffA); PG8_STAGE(PG8_SB(0, 1), cB + hstep, voffB); PG8_STAGE(PG8_SA(0, 1), cA + hstep, voffA);
;     if (wr == 1) PG8_BAR;
;     PG8_WAIT_V(4); PG8_BAR;
;     PG8_STAGE(PG8_SB(1, 0), cB + kstep, voffB); PG8_STAGE(PG8_SA(1, 0), cA + kstep, voffA); PG8_STAGE(PG8_SB(1, 1), cB + hstep + kstep, voffB);
;     PG8_WAIT_V(6); PG8_BAR;
.LBB0_314:
	v_lshrrev_b32_e32 v16, 1, v14
	v_and_b32_e32 v16, 24, v16
	v_and_b32_e32 v15, 15, v14
	v_lshlrev_b32_e32 v17, 1, v16
	v_lshlrev_b32_e32 v14, 2, v14
	s_sext_i32_i16 s55, s22
	v_lshl_or_b32 v142, s24, 6, v15
	v_lshl_or_b32 v15, v15, 6, v17
	s_lshl_b32 s22, s24, 13
	v_and_b32_e32 v14, 32, v14
	v_bitop3_b32 v17, v15, s22, v14 bitop3:0xde
	s_lshl_b32 s22, s23, 5
	s_and_b32 s24, s22, 0x60
	s_add_i32 m0, s21, 0x18000
	v_lshl_add_u64 v[6:7], v[6:7], 0, s[0:1]
	s_xor_b64 s[16:17], s[16:17], -1
	s_lshl_b32 s22, s24, 7
	global_load_lds_dwordx4 v[6:7], off
	v_lshl_add_u64 v[4:5], v[4:5], 0, s[0:1]
	s_add_i32 m0, s21, 0x1a000
	s_add_i32 s49, s21, 0x8000
	s_add_i32 s50, s21, 0xa000
	v_bitop3_b32 v143, v15, s22, v14 bitop3:0xde
	global_load_lds_dwordx4 v[4:5], off
	v_lshl_add_u64 v[2:3], v[2:3], 0, s[0:1]
	s_mov_b32 m0, s49
	s_add_u32 s22, s34, 0x40080
	global_load_lds_dwordx4 v[2:3], off
	v_lshl_add_u64 v[0:1], v[0:1], 0, s[0:1]
	s_mov_b32 m0, s50
	s_addc_u32 s23, s35, 0
	global_load_lds_dwordx4 v[0:1], off
	s_add_i32 m0, s21, 0x1c000
	v_lshl_add_u64 v[0:1], s[22:23], 0, v[48:49]
	global_load_lds_dwordx4 v[0:1], off
	v_lshl_add_u64 v[0:1], s[22:23], 0, v[130:131]
	s_add_i32 m0, s21, 0x1e000
	s_sub_i32 s22, 0, s38
	global_load_lds_dwordx4 v[0:1], off
	s_waitcnt vmcnt(10)
	s_barrier
	v_cvt_f32_u32_e32 v0, s38
	v_and_b32_e32 v1, 1, v12
	s_waitcnt vmcnt(6)
	v_or_b32_e32 v144, s24, v16
	v_rcp_iflag_f32_e32 v0, v0
	s_mov_b32 s51, 0
	v_mov_b32_e32 v137, v49
	v_mov_b32_e32 v139, v49
	v_mul_f32_e32 v0, 0x4f7ffffe, v0
	v_cvt_u32_f32_e32 v0, v0
	v_add_u32_e32 v145, 0, v17
	s_mov_b64 s[72:73], s[56:57]
	s_barrier
	v_readfirstlane_b32 s23, v0
	v_lshlrev_b32_e32 v0, 14, v12
	v_and_b32_e32 v0, 0xffff8000, v0
	v_lshl_add_u32 v0, v11, 11, v0
	v_lshl_or_b32 v0, v1, 6, v0
	v_lshl_add_u32 v136, v13, 1, v0
	v_lshlrev_b32_e32 v0, 14, v8
	v_and_b32_e32 v0, 0xffff8000, v0
	s_mul_i32 s22, s22, s23
	v_lshl_add_u32 v0, v9, 11, v0
	v_and_b32_e32 v1, 1, v8
	s_mul_hi_u32 s22, s23, s22
	v_lshl_or_b32 v0, v1, 6, v0
	s_add_i32 s54, s23, s22
	v_lshl_add_u32 v138, v10, 1, v0
	s_waitcnt vmcnt(0)
	s_branch .LBB0_317

; __device__ __forceinline__ int opaque_tid() { int t; asm volatile("v_mov_b32 %0, %1" : "=v"(t) : "v"((int)threadIdx.x)); return t; }
; #define PG8_STAGE(bufoff, gbase, voff) do { _Pragma("unroll") for (int _i = 0; _i < 2; ++_i) \
;         __builtin_amdgcn_global_load_lds((const unsigned*)((const char*)(gbase) + (voff)[_i]), (PG8_LAS unsigned*)(lds + (bufoff) + ldsw + _i * 8192), 16, 0, 0); } while (0)
; #define PG8_WAIT_V(n) asm volatile("s_waitcnt vmcnt(" #n ")" ::: "memory")
; #define PG8_BAR __builtin_amdgcn_s_barrier()
; template <class Epi, class Sched>
; __device__ __forceinline__ void gemm_phase(PG8_LAS unsigned char* lds, const Gemm g, const Sched& S, const Epi& E) {
;     const int tid = opaque_tid(), wid = __builtin_amdgcn_readfirstlane(tid >> 6), lane = tid & 63, wr = wid >> 2, wc = wid & 3, fr = lane & 15, fq = lane >> 4;
;     const int K = g.K, nt = K / BK, P = g.ldk ? g.ldk : K;
;     unsigned voffA[2], voffB[2];
; #pragma unroll
;     for (int i = 0; i < 2; ++i) { int R, C; stage_rc(tid * 16 + i * 8192, R, C); const int Rb = Epi::PERM ? ((R & ~31) + perm32(R & 31)) : R;
;         voffA[i] = (unsigned)(R * P + C) * 2u; voffB[i] = (unsigned)(Rb * P + C) * 2u; }
;     const size_t kstep = (size_t)(BK * 2);
;     const size_t hstep = (size_t)HALF * P * 2;
;     const size_t tstep = 2 * hstep; const size_t tstepA = g.a_step_rows ? (size_t)g.a_step_rows * P * 2 : tstep; const size_t cstep = (size_t)K * 2;
;     const unsigned ldsw = (unsigned)wid * 1024u;
;     const int aoff = lds_byte(wr * 64 + fr, fq * 8), boff = lds_byte(wc * 32 + fr, fq * 8);
;     ...
;     const char* cA = (const char*)g.A + (size_t)cur.pm * tstepA + (size_t)cur.kc * cstep; const char* cB = (const char*)g.Bt + (size_t)cur.pn * tstep + (size_t)cur.kc * cstep;
;     S.a_ready(cur);
;     PG8_STAGE(PG8_SB(0, 0), cB, voffB); PG8_STAGE(PG8_SA(0, 0), cA, voffA); PG8_STAGE(PG8_SB(0, 1), cB + hstep, voffB); PG8_STAGE(PG8_SA(0, 1), cA + hstep, voffA);
;     if (wr == 1) PG8_BAR;
;     PG8_WAIT_V(4); PG8_BAR;
;     PG8_STAGE(PG8_SB(1, 0), cB + kstep, voffB); PG8_STAGE(PG8_SA(1, 0), cA + kstep, voffA); PG8_STAGE(PG8_SB(1, 1), cB + hstep + kstep, voffB);
;     PG8_WAIT_V(6); PG8_BAR;
.LBB0_331:
	v_lshrrev_b32_e32 v16, 1, v13
	v_and_b32_e32 v138, 24, v16
	v_and_b32_e32 v15, 15, v13
	v_lshlrev_b32_e32 v16, 1, v138
	v_lshlrev_b32_e32 v13, 2, v13
	s_sext_i32_i8 s49, s16
	s_lshl_b32 s10, s10, 6
	s_and_b32 s20, s20, 3
	v_lshl_or_b32 v139, s17, 6, v15
	v_lshl_or_b32 v15, v15, 6, v16
	s_lshl_b32 s16, s17, 13
	v_and_b32_e32 v13, 32, v13
	s_add_i32 m0, s3, 0x18000
	v_lshl_add_u64 v[6:7], v[6:7], 0, s[0:1]
	s_ashr_i32 s11, s10, 31
	v_bitop3_b32 v16, v15, s16, v13 bitop3:0xde
	s_lshl_b32 s16, s20, 12
	global_load_lds_dwordx4 v[6:7], off
	v_lshl_add_u64 v[4:5], v[4:5], 0, s[0:1]
	s_add_i32 m0, s3, 0x1a000
	s_add_i32 s39, s3, 0x8000
	s_add_i32 s42, s3, 0xa000
	v_bitop3_b32 v166, v15, s16, v13 bitop3:0xde
	global_load_lds_dwordx4 v[4:5], off
	v_lshl_add_u64 v[2:3], v[2:3], 0, s[0:1]
	s_mov_b32 m0, s39
	s_add_u32 s16, s12, 0x40080
	global_load_lds_dwordx4 v[2:3], off
	v_lshl_add_u64 v[0:1], v[0:1], 0, s[0:1]
	s_mov_b32 m0, s42
	s_addc_u32 s17, s13, 0
	global_load_lds_dwordx4 v[0:1], off
	s_add_i32 m0, s3, 0x1c000
	v_lshl_add_u64 v[0:1], s[16:17], 0, v[134:135]
	global_load_lds_dwordx4 v[0:1], off
	v_lshl_add_u64 v[0:1], s[16:17], 0, v[130:131]
	s_add_i32 m0, s3, 0x1e000
	s_lshl_b32 s16, s20, 6
	global_load_lds_dwordx4 v[0:1], off
	s_waitcnt vmcnt(10)
	s_barrier
	v_lshlrev_b32_e32 v0, 14, v12
	v_and_b32_e32 v0, 0xffff8000, v0
	v_lshl_add_u32 v0, v11, 11, v0
	v_and_b32_e32 v1, 1, v12
	v_lshl_or_b32 v0, v1, 6, v0
	v_lshl_add_u32 v140, v14, 1, v0
	v_lshlrev_b32_e32 v0, 14, v8
	v_and_b32_e32 v0, 0xffff8000, v0
	s_waitcnt vmcnt(6)
	v_lshl_add_u32 v0, v9, 11, v0
	v_and_b32_e32 v1, 1, v8
	v_lshl_or_b32 v0, v1, 6, v0
	v_mov_b32_e32 v141, v49
	v_lshl_add_u32 v142, v10, 1, v0
	v_mov_b32_e32 v143, v49
	s_mov_b32 s43, 0
	v_add_u32_e32 v167, 0, v16
	s_lshl_b64 s[10:11], s[10:11], 2
	s_lshl_b32 s48, s16, 1
	s_barrier

; #define LAS __attribute__((address_space(3)))
; #define PG8_STAGE(bufoff, gbase, voff) do { _Pragma("unroll") for (int _i = 0; _i < 2; ++_i) \
;         __builtin_amdgcn_global_load_lds((const unsigned*)((const char*)(gbase) + (voff)[_i]), (PG8_LAS unsigned*)(lds + (bufoff) + ldsw + _i * 8192), 16, 0, 0); } while (0)
; #define PG8_WAIT_V(n) asm volatile("s_waitcnt vmcnt(" #n ")" ::: "memory")
; #define PG8_BAR __builtin_amdgcn_s_barrier()
; template <class Epi, class Sched>
; __device__ __forceinline__ void gemm_phase(PG8_LAS unsigned char* lds, const Gemm g, const Sched& S, const Epi& E) {
;     ...
;     PG8_STAGE(PG8_SB(0, 0), cB, voffB); PG8_STAGE(PG8_SA(0, 0), cA, voffA); PG8_STAGE(PG8_SB(0, 1), cB + hstep, voffB); PG8_STAGE(PG8_SA(0, 1), cA + hstep, voffA);
;     if (wr == 1) PG8_BAR;
;     PG8_WAIT_V(4); PG8_BAR;
;     PG8_STAGE(PG8_SB(1, 0), cB + kstep, voffB); PG8_STAGE(PG8_SA(1, 0), cA + kstep, voffA); PG8_STAGE(PG8_SB(1, 1), cB + hstep + kstep, voffB);
;     PG8_WAIT_V(6); PG8_BAR;
;     __device__ __forceinline__ void operator()(const f32x4 (&acc)[2][2][4][2], const pg8::Unit& u, int wr, int wc, int fr, int fq) const {
;         const int cl = 32 * wc + 8 * fq, cv = u.pn * 128 + cl;
; #pragma unroll
;         for (int ai = 0; ai < 2; ++ai) { const int s = 2 * ai + wr;
;             if (fr == 0) { LAS float* p = xb + (s * 2 + 0) * 256 + cl; *(LAS f32x4*)p = acc[ai][0][0][0]; *(LAS f32x4*)(p + 4) = acc[ai][0][0][1]; *(LAS f32x4*)(p + 128) = acc[ai][1][0][0]; *(LAS f32x4*)(p + 132) = acc[ai][1][0][1]; }
;             if (fr == 15) { LAS float* p = xb + (s * 2 + 1) * 256 + cl; *(LAS f32x4*)p = acc[ai][0][3][0]; *(LAS f32x4*)(p + 4) = acc[ai][0][3][1]; *(LAS f32x4*)(p + 128) = acc[ai][1][3][0]; *(LAS f32x4*)(p + 132) = acc[ai][1][3][1]; } }
;         asm volatile("s_waitcnt lgkmcnt(0)\n\ts_barrier\n\ts_barrier" ::: "memory");
;         const int R0 = 254 * u.pm - 1;
;         bool bnd = false;
; #pragma unroll
;         for (int ai = 0; ai < 2; ++ai)
; #pragma unroll
;             for (int m = 0; m < 4; ++m) { const int row = R0 + 128 * ai + 64 * wr + 16 * m + fr;
;                 int pos, last; if (row < ML) { pos = row & (SEQ - 1); last = SEQ - 1; } else { pos = (row - ML) & (CTXL - 1); last = CTXL - 1; }
;                 bnd = bnd || pos == 0 || pos == last || row < 0 || row >= MT; }
.LBB0_381:
	s_add_u32 s20, s8, 0xba00000
	s_addc_u32 s21, s9, 0
	s_mul_i32 s8, s61, 0x12000
	s_mul_hi_i32 s3, s61, 0x12000
	s_add_u32 s30, s40, s8
	v_lshrrev_b32_e32 v15, 1, v14
	s_addc_u32 s31, s41, s3
	s_mul_i32 s8, s61, 0x6000
	v_and_b32_e32 v15, 24, v15
	s_mul_hi_i32 s3, s61, 0x6000
	s_add_u32 s38, s42, s8
	v_and_b32_e32 v175, 15, v14
	v_lshlrev_b32_e32 v16, 1, v15
	v_lshlrev_b32_e32 v14, 2, v14
	s_addc_u32 s39, s43, s3
	v_lshl_or_b32 v16, v175, 6, v16
	s_lshl_b32 s3, s16, 13
	v_and_b32_e32 v14, 32, v14
	v_bitop3_b32 v17, v16, s3, v14 bitop3:0xde
	s_lshl_b32 s3, s17, 5
	s_and_b32 s3, s3, 0x60
	s_add_i32 m0, s37, 0x18000
	v_lshl_add_u64 v[6:7], v[6:7], 0, s[0:1]
	s_lshl_b32 s8, s3, 7
	global_load_lds_dwordx4 v[6:7], off
	v_lshl_add_u64 v[4:5], v[4:5], 0, s[0:1]
	s_add_i32 m0, s37, 0x1a000
	s_add_i32 s25, s37, 0x8000
	s_add_i32 s18, s37, 0xa000
	v_bitop3_b32 v250, v16, s8, v14 bitop3:0xde
	global_load_lds_dwordx4 v[4:5], off
	v_lshl_add_u64 v[2:3], v[2:3], 0, s[0:1]
	s_mov_b32 m0, s25
	s_add_u32 s8, s12, 0x40080
	global_load_lds_dwordx4 v[2:3], off
	v_lshl_add_u64 v[0:1], v[0:1], 0, s[0:1]
	s_mov_b32 m0, s18
	s_addc_u32 s9, s13, 0
	global_load_lds_dwordx4 v[0:1], off
	s_add_i32 m0, s37, 0x1c000
	v_lshl_add_u64 v[0:1], s[8:9], 0, v[178:179]
	global_load_lds_dwordx4 v[0:1], off
	v_lshl_add_u64 v[0:1], s[8:9], 0, v[182:183]
	s_add_i32 m0, s37, 0x1e000
	v_lshl_or_b32 v249, s16, 6, v175
	global_load_lds_dwordx4 v[0:1], off
	s_waitcnt vmcnt(10)
	s_barrier
	v_or_b32_e32 v252, 16, v249
	s_movk_i32 s23, 0xff
	v_or_b32_e32 v225, 32, v249
	v_or_b32_e32 v224, 48, v249
	v_add_u32_e32 v228, 0x90, v249
	v_add_u32_e32 v229, 0xa0, v249
	v_add_u32_e32 v230, 0xb0, v249
	v_cmp_gt_u32_e64 s[46:47], s23, v252
	v_cmp_gt_u32_e64 s[48:49], s23, v225
	v_cmp_gt_u32_e64 s[50:51], s23, v224
	v_cmp_gt_u32_e64 s[54:55], s23, v228
	v_cmp_gt_u32_e64 s[56:57], s23, v229
	v_cmp_gt_u32_e64 s[34:35], s23, v230
	v_readlane_b32 s23, v254, 45
	s_ashr_i32 s23, s23, 31
	v_or_b32_e32 v251, s3, v15
	v_writelane_b32 v254, s23, 57
	s_lshl_b32 s3, s16, 11
	v_readlane_b32 s23, v254, 25
	s_add_i32 s8, s16, 2
	s_add_i32 s3, s23, s3
	s_lshl_b32 s9, s8, 11
	v_writelane_b32 v254, s3, 58
	s_addk_i32 s3, 0x400
	s_max_i32 s17, s16, 1
	s_min_i32 s16, s16, 2
	v_add_u32_e32 v0, -1, v249
	s_movk_i32 s26, 0xfe
	s_max_i32 s22, s8, 1
	s_min_i32 s8, s8, 2
	v_writelane_b32 v254, s3, 59
	s_add_i32 s3, s23, s9
	s_lshl_b32 s17, s17, 11
	s_lshl_b32 s16, s16, 11
	v_cmp_gt_u32_e64 s[44:45], s26, v0
	s_lshl_b32 s22, s22, 11
	s_lshl_b32 s8, s8, 11
	v_add_u32_e32 v0, 0x7f, v249
	v_writelane_b32 v254, s3, 60
	s_addk_i32 s3, 0x400
	v_cmp_gt_u32_e64 s[52:53], s26, v0
	s_add_u32 s26, s30, 0x3000
	v_writelane_b32 v254, s3, 61
	s_addc_u32 s27, s31, 0
	v_writelane_b32 v254, s26, 62
	v_lshlrev_b32_e32 v0, 2, v251
	s_waitcnt vmcnt(6)
	s_mov_b32 s19, 0
	v_writelane_b32 v254, s27, 63
	s_add_u32 s26, s30, 0x6000
	s_addc_u32 s27, s31, 0
	v_writelane_b32 v255, s26, 0
	v_cmp_eq_u32_e64 s[40:41], 0, v175
	v_cmp_eq_u32_e64 s[42:43], 15, v175
	v_writelane_b32 v255, s27, 1
	s_add_u32 s26, s30, 0x9000
	s_addc_u32 s27, s31, 0
	v_writelane_b32 v255, s26, 2
	v_add_u32_e32 v221, 0x80, v249
	v_mov_b32_e32 v185, v49
	v_writelane_b32 v255, s27, 3
	s_add_u32 s26, s30, 0xc000
	s_addc_u32 s27, s31, 0
	v_writelane_b32 v255, s26, 4
	v_mov_b32_e32 v187, v49
	v_add_u32_e32 v242, 0, v17
	v_writelane_b32 v255, s27, 5
	s_add_u32 s26, s30, 0xf000
	v_writelane_b32 v255, s30, 6
	s_addc_u32 s27, s31, 0
	s_barrier
	v_writelane_b32 v255, s31, 7
	v_writelane_b32 v255, s26, 8
	s_nop 1
	v_writelane_b32 v255, s27, 9
	s_add_u32 s26, s38, 0x3000
	v_writelane_b32 v255, s38, 10
	s_addc_u32 s27, s39, 0
	s_add_i32 s3, s23, s17
	s_add_i32 s9, s3, 0xfffffc00
	v_add_u32_e32 v234, s9, v0
	s_add_i32 s9, s23, s16
	v_add_u32_e32 v235, s9, v0
	s_add_i32 s9, s23, s22
	s_add_i32 s16, s9, 0xfffffc00
	s_add_i32 s8, s23, s8
	v_add_u32_e32 v236, s16, v0
	v_add_u32_e32 v237, s8, v0
	v_add_u32_e32 v1, s3, v0
	v_add_u32_e32 v0, s9, v0
	v_add_u32_e32 v240, 0xfffffc10, v0
	v_add_u32_e32 v241, 0xfffffe10, v0
	v_lshlrev_b32_e32 v0, 14, v8
	v_and_b32_e32 v0, 0xffff8000, v0
	v_add_u32_e32 v238, 0xfffffc10, v1
	v_add_u32_e32 v239, 0xfffffe10, v1
	v_lshl_add_u32 v0, v9, 11, v0
	v_and_b32_e32 v1, 1, v8
	v_lshl_or_b32 v0, v1, 6, v0
	v_lshl_add_u32 v184, v10, 1, v0
	v_lshlrev_b32_e32 v0, 14, v11
	v_and_b32_e32 v0, 0xffff8000, v0
	v_writelane_b32 v255, s39, 11
	v_lshl_add_u32 v0, v12, 11, v0
	v_and_b32_e32 v1, 1, v11
	v_writelane_b32 v255, s26, 12
	v_lshl_or_b32 v0, v1, 6, v0
	v_lshl_add_u32 v186, v13, 1, v0
	v_writelane_b32 v255, s27, 13
	s_branch .LBB0_383
